# norm phases: context-row partial-sum fold loads hoisted (2 drains per row instead of 8), on top of attention restructure
# speedup vs baseline: 1.0054x; 1.0054x over previous
.LBB0_102:
	v_cmp_lt_i32_e32 vcc, s90, v121
	v_add_u32_e32 v156, 0xffff8000, v121
	s_and_saveexec_b64 s[2:3], vcc
	s_xor_b64 s[2:3], exec, s[2:3]
	v_lshlrev_b64 v[136:137], 12, v[156:157]
	v_lshl_add_u64 v[18:19], s[26:27], 0, v[136:137]
	s_andn2_saveexec_b64 s[2:3], s[2:3]
	v_lshlrev_b64 v[136:137], 12, v[156:157]
	v_mov_b64_e32 v[18:19], v[130:131]
	s_or_b64 exec, exec, s[2:3]
	v_min_i32_e32 v16, 0x8000, v121
	v_ashrrev_i32_e32 v16, 12, v16
	v_mul_hi_i32_i24_e32 v17, 0x9000, v16
	v_mul_i32_i24_e32 v16, 0x9000, v16
	v_lshl_add_u64 v[16:17], s[56:57], 0, v[16:17]
	v_lshlrev_b32_e32 v156, 2, v122
	v_lshl_add_u64 v[16:17], v[16:17], 0, v[156:157]
	s_waitcnt vmcnt(10)
	v_lshlrev_b32_e32 v32, 4, v120
	v_mov_b32_e32 v33, v157
	v_lshl_add_u64 v[40:41], v[18:19], 0, v[32:33]
	v_add_co_u32_e32 v18, vcc, 0x7000, v16
	global_load_dwordx4 v[72:75], v[40:41], off
	s_nop 0
	v_addc_co_u32_e32 v19, vcc, 0, v17, vcc
	v_add_co_u32_e32 v24, vcc, 0x6000, v16
	v_cmp_lt_i32_e64 s[38:39], s90, v121
	s_nop 0
	v_addc_co_u32_e32 v25, vcc, 0, v17, vcc
	global_load_dwordx4 v[20:23], v[18:19], off
	s_nop 0
	global_load_dwordx4 v[24:27], v[24:25], off
	v_lshl_add_u64 v[34:35], v[124:125], 0, v[136:137]
	v_mov_b32_e32 v112, 0
	v_mov_b32_e32 v114, 0
	v_mov_b32_e32 v115, 0
	v_mov_b32_e32 v116, 0
	v_mov_b32_e32 v117, 0
	s_and_saveexec_b64 s[2:3], s[38:39]
	s_cbranch_execz .LBB0_108
	v_add_co_u32_e32 v246, vcc, 0x800000, v34
	s_nop 1
	v_addc_co_u32_e32 v247, vcc, 0, v35, vcc
	v_add_co_u32_e32 v248, vcc, 0x1000000, v34
	s_nop 1
	v_addc_co_u32_e32 v249, vcc, 0, v35, vcc
	v_add_co_u32_e32 v250, vcc, 0x1800000, v34
	s_nop 1
	v_addc_co_u32_e32 v251, vcc, 0, v35, vcc
	global_load_dwordx4 v[214:217], v[34:35], off
	global_load_dwordx4 v[218:221], v[246:247], off
	global_load_dwordx4 v[222:225], v[248:249], off
	global_load_dwordx4 v[226:229], v[250:251], off
	global_load_dwordx4 v[230:233], v[34:35], off offset:1024
	global_load_dwordx4 v[234:237], v[246:247], off offset:1024
	global_load_dwordx4 v[238:241], v[248:249], off offset:1024
	global_load_dwordx4 v[242:245], v[250:251], off offset:1024
	s_waitcnt vmcnt(0)
	v_pk_add_f32 v[214:215], v[214:215], v[218:219]
	v_pk_add_f32 v[216:217], v[216:217], v[220:221]
	v_pk_add_f32 v[224:225], v[224:225], v[228:229]
	v_pk_add_f32 v[222:223], v[222:223], v[226:227]
	v_pk_add_f32 v[116:117], v[216:217], v[224:225]
	v_pk_add_f32 v[114:115], v[214:215], v[222:223]
.LBB0_108:
	s_or_b64 exec, exec, s[2:3]
	s_mov_b64 s[2:3], 0x7000
	v_lshl_add_u64 v[42:43], v[16:17], 0, s[2:3]
	s_mov_b64 s[2:3], 0x6000
	v_lshl_add_u64 v[48:49], v[16:17], 0, s[2:3]
	global_load_dwordx4 v[88:91], v[40:41], off offset:1024
	global_load_dwordx4 v[28:31], v[42:43], off offset:1024
	global_load_dwordx4 v[16:19], v[48:49], off offset:1024
	v_mov_b32_e32 v113, 0
	v_mov_b32_e32 v140, 0
	v_mov_b32_e32 v141, 0
	s_and_saveexec_b64 s[2:3], s[38:39]
	s_cbranch_execz .LBB0_110
	v_pk_add_f32 v[230:231], v[230:231], v[234:235]
	v_pk_add_f32 v[232:233], v[232:233], v[236:237]
	v_pk_add_f32 v[240:241], v[240:241], v[244:245]
	v_pk_add_f32 v[238:239], v[238:239], v[242:243]
	v_pk_add_f32 v[140:141], v[232:233], v[240:241]
	v_pk_add_f32 v[112:113], v[230:231], v[238:239]
.LBB0_110:
	s_or_b64 exec, exec, s[2:3]
	global_load_dwordx4 v[92:95], v[40:41], off offset:2048
	global_load_dwordx4 v[44:47], v[42:43], off offset:2048
	global_load_dwordx4 v[36:39], v[48:49], off offset:2048
	v_mov_b32_e32 v146, 0
	v_mov_b32_e32 v148, 0
	v_mov_b32_e32 v149, 0
	v_mov_b32_e32 v150, 0
	v_mov_b32_e32 v151, 0
	s_and_saveexec_b64 s[2:3], s[38:39]
	s_cbranch_execz .LBB0_112
	global_load_dwordx4 v[214:217], v[34:35], off offset:2048
	global_load_dwordx4 v[218:221], v[246:247], off offset:2048
	global_load_dwordx4 v[222:225], v[248:249], off offset:2048
	global_load_dwordx4 v[226:229], v[250:251], off offset:2048
	global_load_dwordx4 v[230:233], v[34:35], off offset:3072
	global_load_dwordx4 v[234:237], v[246:247], off offset:3072
	global_load_dwordx4 v[238:241], v[248:249], off offset:3072
	global_load_dwordx4 v[242:245], v[250:251], off offset:3072
	s_waitcnt vmcnt(0)
	v_pk_add_f32 v[214:215], v[214:215], v[218:219]
	v_pk_add_f32 v[216:217], v[216:217], v[220:221]
	v_pk_add_f32 v[224:225], v[224:225], v[228:229]
	v_pk_add_f32 v[222:223], v[222:223], v[226:227]
	v_pk_add_f32 v[150:151], v[216:217], v[224:225]
	v_pk_add_f32 v[148:149], v[214:215], v[222:223]
.LBB0_112:
	s_or_b64 exec, exec, s[2:3]
	global_load_dwordx4 v[100:103], v[40:41], off offset:3072
	global_load_dwordx4 v[68:71], v[42:43], off offset:3072
	global_load_dwordx4 v[64:67], v[48:49], off offset:3072
	v_mov_b32_e32 v147, 0
	v_mov_b32_e32 v162, 0
	v_mov_b32_e32 v163, 0
	s_and_saveexec_b64 s[2:3], s[38:39]
	s_cbranch_execz .LBB0_114
	v_pk_add_f32 v[230:231], v[230:231], v[234:235]
	v_pk_add_f32 v[232:233], v[232:233], v[236:237]
	v_pk_add_f32 v[240:241], v[240:241], v[244:245]
	v_pk_add_f32 v[238:239], v[238:239], v[242:243]
	v_pk_add_f32 v[162:163], v[232:233], v[240:241]
	v_pk_add_f32 v[146:147], v[230:231], v[238:239]
.LBB0_114:
	s_or_b64 exec, exec, s[2:3]
	v_add_u32_e32 v134, s9, v121
	v_readlane_b32 s2, v255, 9
	s_nop 1
	v_cmp_gt_i32_e64 s[40:41], s2, v134
	s_nop 1
	v_cndmask_b32_e64 v40, v121, v134, s[40:41]
	v_cmp_lt_i32_e32 vcc, s90, v40
	v_add_u32_e32 v34, 0xffff8000, v40
	s_and_saveexec_b64 s[2:3], vcc
	s_xor_b64 s[2:3], exec, s[2:3]
	v_mov_b32_e32 v35, v157
	v_lshlrev_b64 v[42:43], 12, v[34:35]
	v_lshl_add_u64 v[48:49], s[26:27], 0, v[42:43]
	s_andn2_saveexec_b64 s[2:3], s[2:3]
	v_ashrrev_i32_e32 v41, 31, v40
	v_lshlrev_b64 v[42:43], 12, v[40:41]
	v_mov_b32_e32 v35, v157
	v_lshl_add_u64 v[48:49], s[48:49], 0, v[42:43]
	v_lshlrev_b64 v[42:43], 12, v[34:35]
	s_or_b64 exec, exec, s[2:3]
	v_min_i32_e32 v33, 0x8000, v40
	v_ashrrev_i32_e32 v33, 12, v33
	v_mul_hi_i32_i24_e32 v35, 0x9000, v33
	v_mul_i32_i24_e32 v34, 0x9000, v33
	v_lshl_add_u64 v[34:35], s[56:57], 0, v[34:35]
	v_lshl_add_u64 v[34:35], v[34:35], 0, v[156:157]
	v_mov_b32_e32 v33, v157
	s_waitcnt vmcnt(16)
	v_lshl_add_u64 v[76:77], v[48:49], 0, v[32:33]
	v_add_co_u32_e32 v32, vcc, 0x7000, v34
	global_load_dwordx4 v[84:87], v[76:77], off
	s_nop 0
	v_addc_co_u32_e32 v33, vcc, 0, v35, vcc
	v_add_co_u32_e32 v52, vcc, 0x6000, v34
	v_cmp_lt_i32_e64 s[42:43], s90, v40
	s_nop 0
	v_addc_co_u32_e32 v53, vcc, 0, v35, vcc
	global_load_dwordx4 v[48:51], v[32:33], off
	s_nop 0
	global_load_dwordx4 v[52:55], v[52:53], off
	v_lshl_add_u64 v[118:119], v[124:125], 0, v[42:43]
	v_mov_b32_e32 v138, 0
	v_mov_b32_e32 v142, 0
	v_mov_b32_e32 v143, 0
	v_mov_b32_e32 v144, 0
	v_mov_b32_e32 v145, 0
	s_and_saveexec_b64 s[2:3], s[42:43]
	s_cbranch_execz .LBB0_120
	v_add_co_u32_e32 v246, vcc, 0x800000, v118
	s_nop 1
	v_addc_co_u32_e32 v247, vcc, 0, v119, vcc
	v_add_co_u32_e32 v248, vcc, 0x1000000, v118
	s_nop 1
	v_addc_co_u32_e32 v249, vcc, 0, v119, vcc
	v_add_co_u32_e32 v250, vcc, 0x1800000, v118
	s_nop 1
	v_addc_co_u32_e32 v251, vcc, 0, v119, vcc
	global_load_dwordx4 v[214:217], v[118:119], off
	global_load_dwordx4 v[218:221], v[246:247], off
	global_load_dwordx4 v[222:225], v[248:249], off
	global_load_dwordx4 v[226:229], v[250:251], off
	global_load_dwordx4 v[230:233], v[118:119], off offset:1024
	global_load_dwordx4 v[234:237], v[246:247], off offset:1024
	global_load_dwordx4 v[238:241], v[248:249], off offset:1024
	global_load_dwordx4 v[242:245], v[250:251], off offset:1024
	s_waitcnt vmcnt(0)
	v_pk_add_f32 v[214:215], v[214:215], v[218:219]
	v_pk_add_f32 v[216:217], v[216:217], v[220:221]
	v_pk_add_f32 v[224:225], v[224:225], v[228:229]
	v_pk_add_f32 v[222:223], v[222:223], v[226:227]
	v_pk_add_f32 v[144:145], v[216:217], v[224:225]
	v_pk_add_f32 v[142:143], v[214:215], v[222:223]
.LBB0_120:
	s_or_b64 exec, exec, s[2:3]
	s_mov_b64 s[2:3], 0x7000
	v_lshl_add_u64 v[78:79], v[34:35], 0, s[2:3]
	s_mov_b64 s[2:3], 0x6000
	v_lshl_add_u64 v[168:169], v[34:35], 0, s[2:3]
	global_load_dwordx4 v[96:99], v[76:77], off offset:1024
	global_load_dwordx4 v[40:43], v[78:79], off offset:1024
	global_load_dwordx4 v[32:35], v[168:169], off offset:1024
	v_mov_b32_e32 v139, 0
	v_mov_b32_e32 v152, 0
	v_mov_b32_e32 v153, 0
	s_and_saveexec_b64 s[2:3], s[42:43]
	s_cbranch_execz .LBB0_122
	v_pk_add_f32 v[230:231], v[230:231], v[234:235]
	v_pk_add_f32 v[232:233], v[232:233], v[236:237]
	v_pk_add_f32 v[240:241], v[240:241], v[244:245]
	v_pk_add_f32 v[238:239], v[238:239], v[242:243]
	v_pk_add_f32 v[152:153], v[232:233], v[240:241]
	v_pk_add_f32 v[138:139], v[230:231], v[238:239]
.LBB0_122:
	s_or_b64 exec, exec, s[2:3]
	global_load_dwordx4 v[104:107], v[76:77], off offset:2048
	global_load_dwordx4 v[60:63], v[78:79], off offset:2048
	global_load_dwordx4 v[56:59], v[168:169], off offset:2048
	v_mov_b32_e32 v154, 0
	v_mov_b32_e32 v164, 0
	v_mov_b32_e32 v165, 0
	v_mov_b32_e32 v166, 0
	v_mov_b32_e32 v167, 0
	s_and_saveexec_b64 s[2:3], s[42:43]
	s_cbranch_execz .LBB0_124
	global_load_dwordx4 v[214:217], v[118:119], off offset:2048
	global_load_dwordx4 v[218:221], v[246:247], off offset:2048
	global_load_dwordx4 v[222:225], v[248:249], off offset:2048
	global_load_dwordx4 v[226:229], v[250:251], off offset:2048
	global_load_dwordx4 v[230:233], v[118:119], off offset:3072
	global_load_dwordx4 v[234:237], v[246:247], off offset:3072
	global_load_dwordx4 v[238:241], v[248:249], off offset:3072
	global_load_dwordx4 v[242:245], v[250:251], off offset:3072
	s_waitcnt vmcnt(0)
	v_pk_add_f32 v[214:215], v[214:215], v[218:219]
	v_pk_add_f32 v[216:217], v[216:217], v[220:221]
	v_pk_add_f32 v[224:225], v[224:225], v[228:229]
	v_pk_add_f32 v[222:223], v[222:223], v[226:227]
	v_pk_add_f32 v[166:167], v[216:217], v[224:225]
	v_pk_add_f32 v[164:165], v[214:215], v[222:223]
.LBB0_124:
	s_or_b64 exec, exec, s[2:3]
	global_load_dwordx4 v[108:111], v[76:77], off offset:3072
	global_load_dwordx4 v[80:83], v[78:79], off offset:3072
	s_nop 0
	global_load_dwordx4 v[76:79], v[168:169], off offset:3072
	v_mov_b32_e32 v155, 0
	v_mov_b32_e32 v168, 0
	v_mov_b32_e32 v169, 0
	s_and_saveexec_b64 s[2:3], s[42:43]
	s_cbranch_execz .LBB0_126
	v_pk_add_f32 v[230:231], v[230:231], v[234:235]
	v_pk_add_f32 v[232:233], v[232:233], v[236:237]
	v_pk_add_f32 v[240:241], v[240:241], v[244:245]
	v_pk_add_f32 v[238:239], v[238:239], v[242:243]
	v_pk_add_f32 v[168:169], v[232:233], v[240:241]
	v_pk_add_f32 v[154:155], v[230:231], v[238:239]

.LBB0_442:
	v_cmp_lt_i32_e32 vcc, s90, v121
	v_add_u32_e32 v156, 0xffff8000, v121
	s_and_saveexec_b64 s[2:3], vcc
	s_xor_b64 s[2:3], exec, s[2:3]
	v_lshlrev_b64 v[136:137], 12, v[156:157]
	v_lshl_add_u64 v[18:19], s[26:27], 0, v[136:137]
	s_andn2_saveexec_b64 s[2:3], s[2:3]
	v_lshlrev_b64 v[136:137], 12, v[156:157]
	v_mov_b64_e32 v[18:19], v[130:131]
	s_or_b64 exec, exec, s[2:3]
	v_min_i32_e32 v16, 0x8000, v121
	v_ashrrev_i32_e32 v16, 12, v16
	v_mul_hi_i32_i24_e32 v17, 0x9000, v16
	v_mul_i32_i24_e32 v16, 0x9000, v16
	v_lshl_add_u64 v[16:17], s[56:57], 0, v[16:17]
	v_lshlrev_b32_e32 v156, 2, v122
	v_lshl_add_u64 v[16:17], v[16:17], 0, v[156:157]
	s_waitcnt vmcnt(0)
	v_lshlrev_b32_e32 v32, 4, v120
	v_mov_b32_e32 v33, v157
	v_lshl_add_u64 v[36:37], v[18:19], 0, v[32:33]
	v_add_co_u32_e32 v18, vcc, 0x4000, v16
	global_load_dwordx4 v[72:75], v[36:37], off
	s_nop 0
	v_addc_co_u32_e32 v19, vcc, 0, v17, vcc
	v_add_co_u32_e32 v24, vcc, 0x3000, v16
	v_cmp_lt_i32_e64 s[38:39], s90, v121
	s_nop 0
	v_addc_co_u32_e32 v25, vcc, 0, v17, vcc
	global_load_dwordx4 v[20:23], v[18:19], off
	s_nop 0
	global_load_dwordx4 v[24:27], v[24:25], off
	v_lshl_add_u64 v[34:35], v[124:125], 0, v[136:137]
	v_mov_b32_e32 v112, 0
	v_mov_b32_e32 v114, 0
	v_mov_b32_e32 v115, 0
	v_mov_b32_e32 v116, 0
	v_mov_b32_e32 v117, 0
	s_and_saveexec_b64 s[2:3], s[38:39]
	s_cbranch_execz .LBB0_448
	v_add_co_u32_e32 v246, vcc, 0x800000, v34
	s_nop 1
	v_addc_co_u32_e32 v247, vcc, 0, v35, vcc
	v_add_co_u32_e32 v248, vcc, 0x1000000, v34
	s_nop 1
	v_addc_co_u32_e32 v249, vcc, 0, v35, vcc
	v_add_co_u32_e32 v250, vcc, 0x1800000, v34
	s_nop 1
	v_addc_co_u32_e32 v251, vcc, 0, v35, vcc
	global_load_dwordx4 v[214:217], v[34:35], off
	global_load_dwordx4 v[218:221], v[246:247], off
	global_load_dwordx4 v[222:225], v[248:249], off
	global_load_dwordx4 v[226:229], v[250:251], off
	global_load_dwordx4 v[230:233], v[34:35], off offset:1024
	global_load_dwordx4 v[234:237], v[246:247], off offset:1024
	global_load_dwordx4 v[238:241], v[248:249], off offset:1024
	global_load_dwordx4 v[242:245], v[250:251], off offset:1024
	s_waitcnt vmcnt(0)
	v_pk_add_f32 v[214:215], v[214:215], v[218:219]
	v_pk_add_f32 v[216:217], v[216:217], v[220:221]
	v_pk_add_f32 v[224:225], v[224:225], v[228:229]
	v_pk_add_f32 v[222:223], v[222:223], v[226:227]
	v_pk_add_f32 v[116:117], v[216:217], v[224:225]
	v_pk_add_f32 v[114:115], v[214:215], v[222:223]
.LBB0_448:
	s_or_b64 exec, exec, s[2:3]
	s_mov_b64 s[2:3], 0x4000
	v_lshl_add_u64 v[38:39], v[16:17], 0, s[2:3]
	v_lshl_add_u64 v[48:49], v[16:17], 0, s[4:5]
	global_load_dwordx4 v[88:91], v[36:37], off offset:1024
	global_load_dwordx4 v[28:31], v[38:39], off offset:1024
	global_load_dwordx4 v[16:19], v[48:49], off offset:1024
	v_mov_b32_e32 v113, 0
	v_mov_b32_e32 v140, 0
	v_mov_b32_e32 v141, 0
	s_and_saveexec_b64 s[2:3], s[38:39]
	s_cbranch_execz .LBB0_450
	v_pk_add_f32 v[230:231], v[230:231], v[234:235]
	v_pk_add_f32 v[232:233], v[232:233], v[236:237]
	v_pk_add_f32 v[240:241], v[240:241], v[244:245]
	v_pk_add_f32 v[238:239], v[238:239], v[242:243]
	v_pk_add_f32 v[140:141], v[232:233], v[240:241]
	v_pk_add_f32 v[112:113], v[230:231], v[238:239]
.LBB0_450:
	s_or_b64 exec, exec, s[2:3]
	global_load_dwordx4 v[92:95], v[36:37], off offset:2048
	global_load_dwordx4 v[44:47], v[38:39], off offset:2048
	global_load_dwordx4 v[40:43], v[48:49], off offset:2048
	v_mov_b32_e32 v146, 0
	v_mov_b32_e32 v148, 0
	v_mov_b32_e32 v149, 0
	v_mov_b32_e32 v150, 0
	v_mov_b32_e32 v151, 0
	s_and_saveexec_b64 s[2:3], s[38:39]
	s_cbranch_execz .LBB0_452
	global_load_dwordx4 v[214:217], v[34:35], off offset:2048
	global_load_dwordx4 v[218:221], v[246:247], off offset:2048
	global_load_dwordx4 v[222:225], v[248:249], off offset:2048
	global_load_dwordx4 v[226:229], v[250:251], off offset:2048
	global_load_dwordx4 v[230:233], v[34:35], off offset:3072
	global_load_dwordx4 v[234:237], v[246:247], off offset:3072
	global_load_dwordx4 v[238:241], v[248:249], off offset:3072
	global_load_dwordx4 v[242:245], v[250:251], off offset:3072
	s_waitcnt vmcnt(0)
	v_pk_add_f32 v[214:215], v[214:215], v[218:219]
	v_pk_add_f32 v[216:217], v[216:217], v[220:221]
	v_pk_add_f32 v[224:225], v[224:225], v[228:229]
	v_pk_add_f32 v[222:223], v[222:223], v[226:227]
	v_pk_add_f32 v[150:151], v[216:217], v[224:225]
	v_pk_add_f32 v[148:149], v[214:215], v[222:223]
.LBB0_452:
	s_or_b64 exec, exec, s[2:3]
	global_load_dwordx4 v[100:103], v[36:37], off offset:3072
	global_load_dwordx4 v[68:71], v[38:39], off offset:3072
	global_load_dwordx4 v[64:67], v[48:49], off offset:3072
	v_mov_b32_e32 v147, 0
	v_mov_b32_e32 v162, 0
	v_mov_b32_e32 v163, 0
	s_and_saveexec_b64 s[2:3], s[38:39]
	s_cbranch_execz .LBB0_454
	v_pk_add_f32 v[230:231], v[230:231], v[234:235]
	v_pk_add_f32 v[232:233], v[232:233], v[236:237]
	v_pk_add_f32 v[240:241], v[240:241], v[244:245]
	v_pk_add_f32 v[238:239], v[238:239], v[242:243]
	v_pk_add_f32 v[162:163], v[232:233], v[240:241]
	v_pk_add_f32 v[146:147], v[230:231], v[238:239]
.LBB0_454:
	s_or_b64 exec, exec, s[2:3]
	v_add_u32_e32 v134, s9, v121
	v_cmp_gt_i32_e64 s[40:41], s77, v134
	s_nop 1
	v_cndmask_b32_e64 v36, v121, v134, s[40:41]
	v_cmp_lt_i32_e32 vcc, s90, v36
	v_add_u32_e32 v34, 0xffff8000, v36
	s_and_saveexec_b64 s[2:3], vcc
	s_xor_b64 s[2:3], exec, s[2:3]
	v_mov_b32_e32 v35, v157
	v_lshlrev_b64 v[38:39], 12, v[34:35]
	v_lshl_add_u64 v[48:49], s[26:27], 0, v[38:39]
	s_andn2_saveexec_b64 s[2:3], s[2:3]
	v_ashrrev_i32_e32 v37, 31, v36
	v_lshlrev_b64 v[38:39], 12, v[36:37]
	v_mov_b32_e32 v35, v157
	v_lshl_add_u64 v[48:49], s[44:45], 0, v[38:39]
	v_lshlrev_b64 v[38:39], 12, v[34:35]
	s_or_b64 exec, exec, s[2:3]
	v_min_i32_e32 v33, 0x8000, v36
	v_ashrrev_i32_e32 v33, 12, v33
	v_mul_hi_i32_i24_e32 v35, 0x9000, v33
	v_mul_i32_i24_e32 v34, 0x9000, v33
	v_lshl_add_u64 v[34:35], s[56:57], 0, v[34:35]
	v_lshl_add_u64 v[34:35], v[34:35], 0, v[156:157]
	v_mov_b32_e32 v33, v157
	v_lshl_add_u64 v[76:77], v[48:49], 0, v[32:33]
	v_add_co_u32_e32 v32, vcc, 0x4000, v34
	global_load_dwordx4 v[84:87], v[76:77], off
	s_nop 0
	v_addc_co_u32_e32 v33, vcc, 0, v35, vcc
	v_add_co_u32_e32 v52, vcc, 0x3000, v34
	v_cmp_lt_i32_e64 s[42:43], s90, v36
	s_nop 0
	v_addc_co_u32_e32 v53, vcc, 0, v35, vcc
	global_load_dwordx4 v[48:51], v[32:33], off
	s_nop 0
	global_load_dwordx4 v[52:55], v[52:53], off
	v_lshl_add_u64 v[118:119], v[124:125], 0, v[38:39]
	v_mov_b32_e32 v138, 0
	v_mov_b32_e32 v142, 0
	v_mov_b32_e32 v143, 0
	v_mov_b32_e32 v144, 0
	v_mov_b32_e32 v145, 0
	s_and_saveexec_b64 s[2:3], s[42:43]
	s_cbranch_execz .LBB0_460
	v_add_co_u32_e32 v246, vcc, 0x800000, v118
	s_nop 1
	v_addc_co_u32_e32 v247, vcc, 0, v119, vcc
	v_add_co_u32_e32 v248, vcc, 0x1000000, v118
	s_nop 1
	v_addc_co_u32_e32 v249, vcc, 0, v119, vcc
	v_add_co_u32_e32 v250, vcc, 0x1800000, v118
	s_nop 1
	v_addc_co_u32_e32 v251, vcc, 0, v119, vcc
	global_load_dwordx4 v[214:217], v[118:119], off
	global_load_dwordx4 v[218:221], v[246:247], off
	global_load_dwordx4 v[222:225], v[248:249], off
	global_load_dwordx4 v[226:229], v[250:251], off
	global_load_dwordx4 v[230:233], v[118:119], off offset:1024
	global_load_dwordx4 v[234:237], v[246:247], off offset:1024
	global_load_dwordx4 v[238:241], v[248:249], off offset:1024
	global_load_dwordx4 v[242:245], v[250:251], off offset:1024
	s_waitcnt vmcnt(0)
	v_pk_add_f32 v[214:215], v[214:215], v[218:219]
	v_pk_add_f32 v[216:217], v[216:217], v[220:221]
	v_pk_add_f32 v[224:225], v[224:225], v[228:229]
	v_pk_add_f32 v[222:223], v[222:223], v[226:227]
	v_pk_add_f32 v[144:145], v[216:217], v[224:225]
	v_pk_add_f32 v[142:143], v[214:215], v[222:223]
.LBB0_460:
	s_or_b64 exec, exec, s[2:3]
	s_mov_b64 s[2:3], 0x4000
	v_lshl_add_u64 v[78:79], v[34:35], 0, s[2:3]
	v_lshl_add_u64 v[168:169], v[34:35], 0, s[4:5]
	global_load_dwordx4 v[96:99], v[76:77], off offset:1024
	global_load_dwordx4 v[36:39], v[78:79], off offset:1024
	global_load_dwordx4 v[32:35], v[168:169], off offset:1024
	v_mov_b32_e32 v139, 0
	v_mov_b32_e32 v152, 0
	v_mov_b32_e32 v153, 0
	s_and_saveexec_b64 s[2:3], s[42:43]
	s_cbranch_execz .LBB0_462
	v_pk_add_f32 v[230:231], v[230:231], v[234:235]
	v_pk_add_f32 v[232:233], v[232:233], v[236:237]
	v_pk_add_f32 v[240:241], v[240:241], v[244:245]
	v_pk_add_f32 v[238:239], v[238:239], v[242:243]
	v_pk_add_f32 v[152:153], v[232:233], v[240:241]
	v_pk_add_f32 v[138:139], v[230:231], v[238:239]

.LBB0_572:
	s_or_b64 exec, exec, s[2:3]
	s_waitcnt vmcnt(0)
	v_min_i32_e32 v16, 0x8000, v121
	v_ashrrev_i32_e32 v16, 12, v16
	v_mul_hi_i32_i24_e32 v17, 0x9000, v16
	v_mul_i32_i24_e32 v16, 0x9000, v16
	v_lshl_add_u64 v[16:17], s[56:57], 0, v[16:17]
	v_lshlrev_b32_e32 v156, 2, v122
	v_lshl_add_u64 v[20:21], v[16:17], 0, v[156:157]
	v_lshlrev_b32_e32 v16, 4, v120
	v_mov_b32_e32 v17, v157
	v_lshl_add_u64 v[22:23], v[18:19], 0, v[16:17]
	v_add_co_u32_e32 v18, vcc, 0x1000, v20
	global_load_dwordx4 v[84:87], v[22:23], off
	s_nop 0
	v_addc_co_u32_e32 v19, vcc, 0, v21, vcc
	global_load_dwordx4 v[32:35], v[18:19], off
	global_load_dwordx4 v[28:31], v[20:21], off
	v_cmp_lt_i32_e64 s[40:41], s90, v121
	s_and_b64 s[6:7], s[44:45], s[40:41]
	v_lshl_add_u64 v[18:19], v[124:125], 0, v[136:137]
	v_mov_b32_e32 v112, 0
	v_mov_b32_e32 v114, 0
	v_mov_b32_e32 v115, 0
	v_mov_b32_e32 v116, 0
	v_mov_b32_e32 v117, 0
	s_and_saveexec_b64 s[2:3], s[6:7]
	s_cbranch_execz .LBB0_574
	v_add_co_u32_e32 v246, vcc, 0x800000, v18
	s_nop 1
	v_addc_co_u32_e32 v247, vcc, 0, v19, vcc
	v_add_co_u32_e32 v248, vcc, 0x1000000, v18
	s_nop 1
	v_addc_co_u32_e32 v249, vcc, 0, v19, vcc
	v_add_co_u32_e32 v250, vcc, 0x1800000, v18
	s_nop 1
	v_addc_co_u32_e32 v251, vcc, 0, v19, vcc
	global_load_dwordx4 v[214:217], v[18:19], off
	global_load_dwordx4 v[218:221], v[246:247], off
	global_load_dwordx4 v[222:225], v[248:249], off
	global_load_dwordx4 v[226:229], v[250:251], off
	global_load_dwordx4 v[230:233], v[18:19], off offset:1024
	global_load_dwordx4 v[234:237], v[246:247], off offset:1024
	global_load_dwordx4 v[238:241], v[248:249], off offset:1024
	global_load_dwordx4 v[242:245], v[250:251], off offset:1024
	s_waitcnt vmcnt(0)
	v_pk_add_f32 v[214:215], v[214:215], v[218:219]
	v_pk_add_f32 v[216:217], v[216:217], v[220:221]
	v_pk_add_f32 v[224:225], v[224:225], v[228:229]
	v_pk_add_f32 v[222:223], v[222:223], v[226:227]
	v_pk_add_f32 v[116:117], v[216:217], v[224:225]
	v_pk_add_f32 v[114:115], v[214:215], v[222:223]
.LBB0_574:
	s_or_b64 exec, exec, s[2:3]
	s_mov_b64 s[2:3], 0x1000
	s_waitcnt vmcnt(0)
	v_lshl_add_u64 v[36:37], v[20:21], 0, s[2:3]
	global_load_dwordx4 v[92:95], v[22:23], off offset:1024
	global_load_dwordx4 v[60:63], v[36:37], off offset:1024
	global_load_dwordx4 v[24:27], v[20:21], off offset:1024
	v_mov_b32_e32 v113, 0
	v_mov_b32_e32 v144, 0
	v_mov_b32_e32 v145, 0
	s_and_saveexec_b64 s[2:3], s[6:7]
	s_cbranch_execz .LBB0_576
	v_pk_add_f32 v[230:231], v[230:231], v[234:235]
	v_pk_add_f32 v[232:233], v[232:233], v[236:237]
	v_pk_add_f32 v[240:241], v[240:241], v[244:245]
	v_pk_add_f32 v[238:239], v[238:239], v[242:243]
	v_pk_add_f32 v[144:145], v[232:233], v[240:241]
	v_pk_add_f32 v[112:113], v[230:231], v[238:239]
.LBB0_576:
	s_or_b64 exec, exec, s[2:3]
	global_load_dwordx4 v[96:99], v[22:23], off offset:2048
	global_load_dwordx4 v[56:59], v[36:37], off offset:2048
	global_load_dwordx4 v[52:55], v[20:21], off offset:2048
	v_mov_b32_e32 v148, 0
	v_mov_b32_e32 v150, 0
	v_mov_b32_e32 v151, 0
	v_mov_b32_e32 v152, 0
	v_mov_b32_e32 v153, 0
	s_and_saveexec_b64 s[2:3], s[6:7]
	s_cbranch_execz .LBB0_578
	global_load_dwordx4 v[214:217], v[18:19], off offset:2048
	global_load_dwordx4 v[218:221], v[246:247], off offset:2048
	global_load_dwordx4 v[222:225], v[248:249], off offset:2048
	global_load_dwordx4 v[226:229], v[250:251], off offset:2048
	global_load_dwordx4 v[230:233], v[18:19], off offset:3072
	global_load_dwordx4 v[234:237], v[246:247], off offset:3072
	global_load_dwordx4 v[238:241], v[248:249], off offset:3072
	global_load_dwordx4 v[242:245], v[250:251], off offset:3072
	s_waitcnt vmcnt(0)
	v_pk_add_f32 v[214:215], v[214:215], v[218:219]
	v_pk_add_f32 v[216:217], v[216:217], v[220:221]
	v_pk_add_f32 v[224:225], v[224:225], v[228:229]
	v_pk_add_f32 v[222:223], v[222:223], v[226:227]
	v_pk_add_f32 v[152:153], v[216:217], v[224:225]
	v_pk_add_f32 v[150:151], v[214:215], v[222:223]
.LBB0_578:
	s_or_b64 exec, exec, s[2:3]
	global_load_dwordx4 v[104:107], v[22:23], off offset:3072
	global_load_dwordx4 v[68:71], v[36:37], off offset:3072
	global_load_dwordx4 v[64:67], v[20:21], off offset:3072
	v_mov_b32_e32 v149, 0
	v_mov_b32_e32 v166, 0
	v_mov_b32_e32 v167, 0
	s_and_saveexec_b64 s[2:3], s[6:7]
	s_cbranch_execz .LBB0_580
	v_pk_add_f32 v[230:231], v[230:231], v[234:235]
	v_pk_add_f32 v[232:233], v[232:233], v[236:237]
	v_pk_add_f32 v[240:241], v[240:241], v[244:245]
	v_pk_add_f32 v[238:239], v[238:239], v[242:243]
	v_pk_add_f32 v[166:167], v[232:233], v[240:241]
	v_pk_add_f32 v[148:149], v[230:231], v[238:239]
.LBB0_580:
	s_or_b64 exec, exec, s[2:3]
	v_add_u32_e32 v134, s9, v121
	v_cmp_gt_i32_e64 s[38:39], s77, v134
	s_nop 1
	v_cndmask_b32_e64 v18, v121, v134, s[38:39]
	v_cmp_lt_i32_e32 vcc, s90, v18
	v_add_u32_e32 v36, 0xffff8000, v18
	s_and_saveexec_b64 s[2:3], vcc
	s_xor_b64 s[2:3], exec, s[2:3]
	v_mov_b32_e32 v37, v157
	v_lshlrev_b64 v[20:21], 12, v[36:37]
	v_lshl_add_u64 v[22:23], s[30:31], 0, v[20:21]
	s_andn2_saveexec_b64 s[2:3], s[2:3]
	v_ashrrev_i32_e32 v19, 31, v18
	v_lshlrev_b64 v[20:21], 12, v[18:19]
	v_mov_b32_e32 v37, v157
	v_lshl_add_u64 v[22:23], s[36:37], 0, v[20:21]
	v_lshlrev_b64 v[20:21], 12, v[36:37]
	s_or_b64 exec, exec, s[2:3]
	v_min_i32_e32 v17, 0x8000, v18
	v_ashrrev_i32_e32 v17, 12, v17
	v_mul_hi_i32_i24_e32 v37, 0x9000, v17
	v_mul_i32_i24_e32 v36, 0x9000, v17
	v_lshl_add_u64 v[36:37], s[56:57], 0, v[36:37]
	v_lshl_add_u64 v[72:73], v[36:37], 0, v[156:157]
	v_mov_b32_e32 v17, v157
	v_lshl_add_u64 v[74:75], v[22:23], 0, v[16:17]
	v_add_co_u32_e32 v16, vcc, 0x1000, v72
	global_load_dwordx4 v[80:83], v[74:75], off
	s_nop 0
	v_addc_co_u32_e32 v17, vcc, 0, v73, vcc
	global_load_dwordx4 v[48:51], v[16:17], off
	global_load_dwordx4 v[40:43], v[72:73], off
	v_cmp_lt_i32_e32 vcc, s90, v18
	s_and_b64 s[6:7], s[44:45], vcc
	v_lshl_add_u64 v[118:119], v[124:125], 0, v[20:21]
	v_mov_b32_e32 v142, 0
	v_mov_b32_e32 v138, 0
	v_mov_b32_e32 v139, 0
	v_mov_b32_e32 v140, 0
	v_mov_b32_e32 v141, 0
	s_and_saveexec_b64 s[2:3], s[6:7]
	s_cbranch_execz .LBB0_586
	v_add_co_u32_e32 v246, vcc, 0x800000, v118
	s_nop 1
	v_addc_co_u32_e32 v247, vcc, 0, v119, vcc
	v_add_co_u32_e32 v248, vcc, 0x1000000, v118
	s_nop 1
	v_addc_co_u32_e32 v249, vcc, 0, v119, vcc
	v_add_co_u32_e32 v250, vcc, 0x1800000, v118
	s_nop 1
	v_addc_co_u32_e32 v251, vcc, 0, v119, vcc
	global_load_dwordx4 v[214:217], v[118:119], off
	global_load_dwordx4 v[218:221], v[246:247], off
	global_load_dwordx4 v[222:225], v[248:249], off
	global_load_dwordx4 v[226:229], v[250:251], off
	global_load_dwordx4 v[230:233], v[118:119], off offset:1024
	global_load_dwordx4 v[234:237], v[246:247], off offset:1024
	global_load_dwordx4 v[238:241], v[248:249], off offset:1024
	global_load_dwordx4 v[242:245], v[250:251], off offset:1024
	s_waitcnt vmcnt(0)
	v_pk_add_f32 v[214:215], v[214:215], v[218:219]
	v_pk_add_f32 v[216:217], v[216:217], v[220:221]
	v_pk_add_f32 v[224:225], v[224:225], v[228:229]
	v_pk_add_f32 v[222:223], v[222:223], v[226:227]
	v_pk_add_f32 v[140:141], v[216:217], v[224:225]
	v_pk_add_f32 v[138:139], v[214:215], v[222:223]
.LBB0_586:
	s_or_b64 exec, exec, s[2:3]
	s_mov_b64 s[2:3], 0x1000
	v_lshl_add_u64 v[76:77], v[72:73], 0, s[2:3]
	global_load_dwordx4 v[88:91], v[74:75], off offset:1024
	global_load_dwordx4 v[20:23], v[76:77], off offset:1024
	global_load_dwordx4 v[16:19], v[72:73], off offset:1024
	v_mov_b32_e32 v143, 0
	v_mov_b32_e32 v146, 0
	v_mov_b32_e32 v147, 0
	s_and_saveexec_b64 s[2:3], s[6:7]
	s_cbranch_execz .LBB0_588
	v_pk_add_f32 v[230:231], v[230:231], v[234:235]
	v_pk_add_f32 v[232:233], v[232:233], v[236:237]
	v_pk_add_f32 v[240:241], v[240:241], v[244:245]
	v_pk_add_f32 v[238:239], v[238:239], v[242:243]
	v_pk_add_f32 v[146:147], v[232:233], v[240:241]
	v_pk_add_f32 v[142:143], v[230:231], v[238:239]
.LBB0_588:
	s_or_b64 exec, exec, s[2:3]
	global_load_dwordx4 v[100:103], v[74:75], off offset:2048
	global_load_dwordx4 v[44:47], v[76:77], off offset:2048
	global_load_dwordx4 v[36:39], v[72:73], off offset:2048
	v_mov_b32_e32 v154, 0
	v_mov_b32_e32 v162, 0
	v_mov_b32_e32 v163, 0
	v_mov_b32_e32 v164, 0
	v_mov_b32_e32 v165, 0
	s_and_saveexec_b64 s[2:3], s[6:7]
	s_cbranch_execz .LBB0_590
	global_load_dwordx4 v[214:217], v[118:119], off offset:2048
	global_load_dwordx4 v[218:221], v[246:247], off offset:2048
	global_load_dwordx4 v[222:225], v[248:249], off offset:2048
	global_load_dwordx4 v[226:229], v[250:251], off offset:2048
	global_load_dwordx4 v[230:233], v[118:119], off offset:3072
	global_load_dwordx4 v[234:237], v[246:247], off offset:3072
	global_load_dwordx4 v[238:241], v[248:249], off offset:3072
	global_load_dwordx4 v[242:245], v[250:251], off offset:3072
	s_waitcnt vmcnt(0)
	v_pk_add_f32 v[214:215], v[214:215], v[218:219]
	v_pk_add_f32 v[216:217], v[216:217], v[220:221]
	v_pk_add_f32 v[224:225], v[224:225], v[228:229]
	v_pk_add_f32 v[222:223], v[222:223], v[226:227]
	v_pk_add_f32 v[164:165], v[216:217], v[224:225]
	v_pk_add_f32 v[162:163], v[214:215], v[222:223]
.LBB0_590:
	s_or_b64 exec, exec, s[2:3]
	global_load_dwordx4 v[108:111], v[74:75], off offset:3072
	s_nop 0
	global_load_dwordx4 v[76:79], v[76:77], off offset:3072
	s_nop 0
	global_load_dwordx4 v[72:75], v[72:73], off offset:3072
	v_mov_b32_e32 v155, 0
	v_mov_b32_e32 v168, 0
	v_mov_b32_e32 v169, 0
	s_and_saveexec_b64 s[2:3], s[6:7]
	s_cbranch_execz .LBB0_592
	v_pk_add_f32 v[230:231], v[230:231], v[234:235]
	v_pk_add_f32 v[232:233], v[232:233], v[236:237]
	v_pk_add_f32 v[240:241], v[240:241], v[244:245]
	v_pk_add_f32 v[238:239], v[238:239], v[242:243]
	v_pk_add_f32 v[168:169], v[232:233], v[240:241]
	v_pk_add_f32 v[154:155], v[230:231], v[238:239]
